# grid-barrier spin loops poll every 6x64 cycles instead of 1x64 (less L2 polling traffic while stragglers finish)
# baseline (speedup 1.0000x reference)
; __device__ __forceinline__ unsigned xb_ld(unsigned* p)              { return __hip_atomic_load(p, __ATOMIC_RELAXED, __HIP_MEMORY_SCOPE_AGENT); }
; __device__ __forceinline__ void xcd_barrier_complete(unsigned* bar, unsigned x, unsigned& nloc, unsigned& nx) {
;     const unsigned G = gridDim.x * gridDim.y * gridDim.z;
;     unsigned sum, cnt, mine, sp = 0u;
;     for (;;) {
;         sum = 0u; cnt = 0u; mine = 0u;
; #pragma unroll
;         for (unsigned j = 0; j < 16; ++j) { const unsigned c = xb_ld(&bar[XB_XCNT(j)]); sum += c; cnt += (c > 0u) ? 1u : 0u; mine = (j == x) ? c : mine; }
;         if (sum == G) break;
;         __builtin_amdgcn_s_sleep(1);
;         if ((++sp & 255u) == 0u) { if (xb_ld(&bar[XB_TMO])) break; if (sp > XB_SPIN_CAP) { atomicAdd(&bar[XB_TMO], 1u); break; } }
;     }
;     nloc = mine > 0u ? mine : 1u; nx = cnt > 0u ? cnt : 1u;
.LBB0_68:
	global_load_dword v17, v1, s[12:13] offset:1024 sc1
	global_load_dword v0, v1, s[12:13] offset:1280 sc1
	s_waitcnt lgkmcnt(0)
	global_load_dword v2, v1, s[12:13] offset:1536 sc1
	global_load_dword v3, v1, s[12:13] offset:1792 sc1
	global_load_dword v4, v1, s[12:13] offset:2048 sc1
	global_load_dword v5, v1, s[12:13] offset:2304 sc1
	global_load_dword v6, v1, s[12:13] offset:2560 sc1
	global_load_dword v7, v1, s[12:13] offset:2816 sc1
	global_load_dword v8, v1, s[12:13] offset:3072 sc1
	global_load_dword v9, v1, s[12:13] offset:3328 sc1
	global_load_dword v10, v1, s[12:13] offset:3584 sc1
	global_load_dword v11, v1, s[12:13] offset:3840 sc1
	global_load_dword v12, v1, s[14:15] sc1
	global_load_dword v13, v1, s[16:17] sc1
	global_load_dword v14, v1, s[18:19] sc1
	global_load_dword v15, v1, s[20:21] sc1
	v_readlane_b32 s4, v254, 27
	s_mov_b64 s[22:23], -1
	s_mov_b64 s[24:25], -1
	s_waitcnt vmcnt(14)
	v_add_u32_e32 v18, v0, v17
	s_waitcnt vmcnt(13)
	v_add_u32_e32 v18, v18, v2
	s_waitcnt vmcnt(12)
	v_add_u32_e32 v18, v18, v3
	s_waitcnt vmcnt(11)
	v_add_u32_e32 v18, v18, v4
	s_waitcnt vmcnt(10)
	v_add_u32_e32 v18, v18, v5
	s_waitcnt vmcnt(9)
	v_add_u32_e32 v18, v18, v6
	s_waitcnt vmcnt(8)
	v_add_u32_e32 v18, v18, v7
	s_waitcnt vmcnt(7)
	v_add_u32_e32 v18, v18, v8
	s_waitcnt vmcnt(6)
	v_add_u32_e32 v18, v18, v9
	s_waitcnt vmcnt(5)
	v_add_u32_e32 v18, v18, v10
	s_waitcnt vmcnt(4)
	v_add_u32_e32 v18, v18, v11
	s_waitcnt vmcnt(3)
	v_add_u32_e32 v18, v18, v12
	s_waitcnt vmcnt(2)
	v_add_u32_e32 v18, v18, v13
	s_waitcnt vmcnt(1)
	v_add_u32_e32 v18, v18, v14
	s_waitcnt vmcnt(0)
	v_add_u32_e32 v18, v18, v15
	v_cmp_eq_u32_e32 vcc, s4, v18
	s_cbranch_vccnz .LBB0_67
	s_and_b32 s4, s3, 0xff
	s_cmp_eq_u32 s4, 0
	s_mov_b64 s[26:27], -1
	s_sleep 6
	s_cbranch_scc0 .LBB0_72
	global_load_dword v18, v1, s[12:13] offset:512 sc1
	s_waitcnt vmcnt(0)
	v_cmp_eq_u32_e32 vcc, 0, v18
	s_cbranch_vccnz .LBB0_74
	s_mov_b64 s[26:27], 0

; __device__ __forceinline__ unsigned xb_ld(unsigned* p)              { return __hip_atomic_load(p, __ATOMIC_RELAXED, __HIP_MEMORY_SCOPE_AGENT); }
; __device__ __forceinline__ unsigned xb_add(unsigned* p, unsigned v) { return __hip_atomic_fetch_add(p, v, __ATOMIC_RELAXED, __HIP_MEMORY_SCOPE_AGENT); }
; #define XB_SPIN(cond, bar) do { unsigned _sp = 0; while (cond) { __builtin_amdgcn_s_sleep(1); \
;     if ((++_sp & 255u) == 0u) { if (xb_ld(&(bar)[XB_TMO])) break; if (_sp > XB_SPIN_CAP) { atomicAdd(&(bar)[XB_TMO], 1u); break; } } } } while (0)
; __device__ __forceinline__ void xcd_barrier(const XcdBarrier& b) {
;     ...
;             else XB_SPIN(xb_ld(&bar[XB_TOPGEN]) == tg, bar);
;             __builtin_amdgcn_fence(__ATOMIC_ACQUIRE, "agent");
;             xb_add(&bar[XB_XGEN(b.x)], 1u);
;             asm volatile("s_waitcnt vmcnt(0)" ::: "memory");
;         } else {
;             XB_SPIN(xb_ld(&bar[XB_XGEN(b.x)]) == gen, bar);
.LBB0_86:
	s_and_b32 s3, s2, 0xff
	s_mov_b64 s[26:27], -1
	s_cmp_lg_u32 s3, 0
	s_mov_b64 s[30:31], -1
	s_sleep 6
	s_cbranch_scc1 .LBB0_89
	global_load_dword v2, v1, s[12:13] offset:512 sc1
	s_waitcnt vmcnt(0)
	v_cmp_eq_u32_e32 vcc, 0, v2
	s_cbranch_vccnz .LBB0_91
	s_mov_b64 s[30:31], 0
	s_mov_b64 s[28:29], -1

; __device__ __forceinline__ unsigned xb_ld(unsigned* p)              { return __hip_atomic_load(p, __ATOMIC_RELAXED, __HIP_MEMORY_SCOPE_AGENT); }
; __device__ __forceinline__ unsigned xb_add(unsigned* p, unsigned v) { return __hip_atomic_fetch_add(p, v, __ATOMIC_RELAXED, __HIP_MEMORY_SCOPE_AGENT); }
; #define XB_SPIN(cond, bar) do { unsigned _sp = 0; while (cond) { __builtin_amdgcn_s_sleep(1); \
;     if ((++_sp & 255u) == 0u) { if (xb_ld(&(bar)[XB_TMO])) break; if (_sp > XB_SPIN_CAP) { atomicAdd(&(bar)[XB_TMO], 1u); break; } } } } while (0)
; __device__ __forceinline__ void xcd_barrier(const XcdBarrier& b) {
;     ...
;             else XB_SPIN(xb_ld(&bar[XB_TOPGEN]) == tg, bar);
;             __builtin_amdgcn_fence(__ATOMIC_ACQUIRE, "agent");
;             xb_add(&bar[XB_XGEN(b.x)], 1u);
;             asm volatile("s_waitcnt vmcnt(0)" ::: "memory");
;         } else {
;             XB_SPIN(xb_ld(&bar[XB_XGEN(b.x)]) == gen, bar);
.LBB0_103:
	s_and_b32 s3, s2, 0xff
	s_mov_b64 s[26:27], -1
	s_cmp_lg_u32 s3, 0
	s_mov_b64 s[30:31], -1
	s_sleep 6
	s_cbranch_scc1 .LBB0_106
	global_load_dword v2, v1, s[20:21] sc1
	s_waitcnt vmcnt(0)
	v_cmp_eq_u32_e32 vcc, 0, v2
	s_cbranch_vccnz .LBB0_108
	s_mov_b64 s[30:31], 0
	s_mov_b64 s[28:29], -1

; #define GSYNC() do { KP Pb_ = KARGS(); XcdBarrier b_; b_.bar = (unsigned*)(Pb_->ws + WS_CTL); b_.x = xb_xcc_id(); b_.st = (volatile LAS unsigned*)(lds + LDS_BAR_OFF); xcd_barrier(b_); } while (0)
; __global__ void __launch_bounds__(NTHR, 2) hybrid_fwd(Args args) {
;     ...
;         if (layer == 0) grid.sync(); else GSYNC();
.LBB0_126:
	s_sleep 6
	global_load_dword v2, v1, s[12:13] offset:32 sc1
	s_waitcnt vmcnt(0)
	v_and_b32_e32 v2, 0xffff0000, v2
	v_cmp_ne_u32_e32 vcc, v2, v0
	s_or_b64 s[14:15], vcc, s[14:15]
	s_andn2_b64 exec, exec, s[14:15]
	s_cbranch_execnz .LBB0_126

; __device__ __forceinline__ unsigned xb_ld(unsigned* p)              { return __hip_atomic_load(p, __ATOMIC_RELAXED, __HIP_MEMORY_SCOPE_AGENT); }
; __device__ __forceinline__ void xcd_barrier_complete(unsigned* bar, unsigned x, unsigned& nloc, unsigned& nx) {
;     const unsigned G = gridDim.x * gridDim.y * gridDim.z;
;     unsigned sum, cnt, mine, sp = 0u;
;     for (;;) {
;         sum = 0u; cnt = 0u; mine = 0u;
; #pragma unroll
;         for (unsigned j = 0; j < 16; ++j) { const unsigned c = xb_ld(&bar[XB_XCNT(j)]); sum += c; cnt += (c > 0u) ? 1u : 0u; mine = (j == x) ? c : mine; }
;         if (sum == G) break;
;         __builtin_amdgcn_s_sleep(1);
;         if ((++sp & 255u) == 0u) { if (xb_ld(&bar[XB_TMO])) break; if (sp > XB_SPIN_CAP) { atomicAdd(&bar[XB_TMO], 1u); break; } }
;     }
;     nloc = mine > 0u ? mine : 1u; nx = cnt > 0u ? cnt : 1u;
.LBB0_190:
	global_load_dword v17, v1, s[10:11] offset:1024 sc1
	global_load_dword v0, v1, s[10:11] offset:1280 sc1
	s_waitcnt lgkmcnt(0)
	global_load_dword v2, v1, s[10:11] offset:1536 sc1
	global_load_dword v3, v1, s[10:11] offset:1792 sc1
	global_load_dword v4, v1, s[10:11] offset:2048 sc1
	global_load_dword v5, v1, s[10:11] offset:2304 sc1
	global_load_dword v6, v1, s[10:11] offset:2560 sc1
	global_load_dword v7, v1, s[10:11] offset:2816 sc1
	global_load_dword v8, v1, s[10:11] offset:3072 sc1
	global_load_dword v9, v1, s[10:11] offset:3328 sc1
	global_load_dword v10, v1, s[10:11] offset:3584 sc1
	global_load_dword v11, v1, s[10:11] offset:3840 sc1
	global_load_dword v12, v1, s[12:13] sc1
	global_load_dword v13, v1, s[14:15] sc1
	global_load_dword v14, v1, s[16:17] sc1
	global_load_dword v15, v1, s[18:19] sc1
	v_readlane_b32 s4, v254, 27
	s_mov_b64 s[20:21], -1
	s_mov_b64 s[22:23], -1
	s_waitcnt vmcnt(14)
	v_add_u32_e32 v18, v0, v17
	s_waitcnt vmcnt(13)
	v_add_u32_e32 v18, v18, v2
	s_waitcnt vmcnt(12)
	v_add_u32_e32 v18, v18, v3
	s_waitcnt vmcnt(11)
	v_add_u32_e32 v18, v18, v4
	s_waitcnt vmcnt(10)
	v_add_u32_e32 v18, v18, v5
	s_waitcnt vmcnt(9)
	v_add_u32_e32 v18, v18, v6
	s_waitcnt vmcnt(8)
	v_add_u32_e32 v18, v18, v7
	s_waitcnt vmcnt(7)
	v_add_u32_e32 v18, v18, v8
	s_waitcnt vmcnt(6)
	v_add_u32_e32 v18, v18, v9
	s_waitcnt vmcnt(5)
	v_add_u32_e32 v18, v18, v10
	s_waitcnt vmcnt(4)
	v_add_u32_e32 v18, v18, v11
	s_waitcnt vmcnt(3)
	v_add_u32_e32 v18, v18, v12
	s_waitcnt vmcnt(2)
	v_add_u32_e32 v18, v18, v13
	s_waitcnt vmcnt(1)
	v_add_u32_e32 v18, v18, v14
	s_waitcnt vmcnt(0)
	v_add_u32_e32 v18, v18, v15
	v_cmp_eq_u32_e32 vcc, s4, v18
	s_cbranch_vccnz .LBB0_189
	s_and_b32 s4, s3, 0xff
	s_cmp_eq_u32 s4, 0
	s_mov_b64 s[24:25], -1
	s_sleep 6
	s_cbranch_scc0 .LBB0_194
	global_load_dword v18, v1, s[10:11] offset:512 sc1
	s_waitcnt vmcnt(0)
	v_cmp_eq_u32_e32 vcc, 0, v18
	s_cbranch_vccnz .LBB0_196
	s_mov_b64 s[24:25], 0

; __device__ __forceinline__ unsigned xb_ld(unsigned* p)              { return __hip_atomic_load(p, __ATOMIC_RELAXED, __HIP_MEMORY_SCOPE_AGENT); }
; __device__ __forceinline__ unsigned xb_add(unsigned* p, unsigned v) { return __hip_atomic_fetch_add(p, v, __ATOMIC_RELAXED, __HIP_MEMORY_SCOPE_AGENT); }
; #define XB_SPIN(cond, bar) do { unsigned _sp = 0; while (cond) { __builtin_amdgcn_s_sleep(1); \
;     if ((++_sp & 255u) == 0u) { if (xb_ld(&(bar)[XB_TMO])) break; if (_sp > XB_SPIN_CAP) { atomicAdd(&(bar)[XB_TMO], 1u); break; } } } } while (0)
; __device__ __forceinline__ void xcd_barrier(const XcdBarrier& b) {
;     ...
;             else XB_SPIN(xb_ld(&bar[XB_TOPGEN]) == tg, bar);
;             __builtin_amdgcn_fence(__ATOMIC_ACQUIRE, "agent");
;             xb_add(&bar[XB_XGEN(b.x)], 1u);
;             asm volatile("s_waitcnt vmcnt(0)" ::: "memory");
;         } else {
;             XB_SPIN(xb_ld(&bar[XB_XGEN(b.x)]) == gen, bar);
.LBB0_208:
	s_and_b32 s3, s2, 0xff
	s_mov_b64 s[24:25], -1
	s_cmp_lg_u32 s3, 0
	s_mov_b64 s[28:29], -1
	s_sleep 6
	s_cbranch_scc1 .LBB0_211
	global_load_dword v2, v1, s[10:11] offset:512 sc1
	s_waitcnt vmcnt(0)
	v_cmp_eq_u32_e32 vcc, 0, v2
	s_cbranch_vccnz .LBB0_213
	s_mov_b64 s[28:29], 0
	s_mov_b64 s[26:27], -1

; __device__ __forceinline__ unsigned xb_ld(unsigned* p)              { return __hip_atomic_load(p, __ATOMIC_RELAXED, __HIP_MEMORY_SCOPE_AGENT); }
; __device__ __forceinline__ unsigned xb_add(unsigned* p, unsigned v) { return __hip_atomic_fetch_add(p, v, __ATOMIC_RELAXED, __HIP_MEMORY_SCOPE_AGENT); }
; #define XB_SPIN(cond, bar) do { unsigned _sp = 0; while (cond) { __builtin_amdgcn_s_sleep(1); \
;     if ((++_sp & 255u) == 0u) { if (xb_ld(&(bar)[XB_TMO])) break; if (_sp > XB_SPIN_CAP) { atomicAdd(&(bar)[XB_TMO], 1u); break; } } } } while (0)
; __device__ __forceinline__ void xcd_barrier(const XcdBarrier& b) {
;     ...
;             else XB_SPIN(xb_ld(&bar[XB_TOPGEN]) == tg, bar);
;             __builtin_amdgcn_fence(__ATOMIC_ACQUIRE, "agent");
;             xb_add(&bar[XB_XGEN(b.x)], 1u);
;             asm volatile("s_waitcnt vmcnt(0)" ::: "memory");
;         } else {
;             XB_SPIN(xb_ld(&bar[XB_XGEN(b.x)]) == gen, bar);
.LBB0_225:
	s_and_b32 s3, s2, 0xff
	s_mov_b64 s[24:25], -1
	s_cmp_lg_u32 s3, 0
	s_mov_b64 s[28:29], -1
	s_sleep 6
	s_cbranch_scc1 .LBB0_228
	global_load_dword v2, v1, s[18:19] sc1
	s_waitcnt vmcnt(0)
	v_cmp_eq_u32_e32 vcc, 0, v2
	s_cbranch_vccnz .LBB0_230
	s_mov_b64 s[28:29], 0
	s_mov_b64 s[26:27], -1
